# unit headers: removed the generic divide-by-gsz (gsz is always 1: wgm=1) from the 8 per-tile next-unit index computations (34 -> 4 instrs incl. v_rcp + readfirstlane chain)
# baseline (speedup 1.0000x reference)
.LBB0_215:
	s_ashr_i32 s7, s7, 3
	s_add_i32 s7, s25, s7
	s_ashr_i32 s22, s7, 31
	s_lshr_b32 s22, s22, 29
	s_add_i32 s22, s7, s22
	s_ashr_i32 s23, s22, 3
	s_and_b32 s22, s22, -8
	s_sub_i32 s7, s7, s22
	s_mov_b32 s22, s7
	s_mov_b32 s24, s23

.LBB0_469:
	s_ashr_i32 s18, s20, 3
	s_add_i32 s18, s22, s18
	s_ashr_i32 s19, s18, 31
	s_lshr_b32 s19, s19, 30
	s_add_i32 s19, s18, s19
	s_ashr_i32 s20, s19, 2
	s_and_b32 s19, s19, -4
	s_sub_i32 s19, s18, s19
	s_mov_b32 s18, s19

.LBB0_471:
	s_add_u32 s34, s30, 0xfffc0080
	s_addc_u32 s35, s31, -1
	s_cmp_eq_u32 s69, 12
	s_cselect_b32 s37, s21, s35
	s_cselect_b32 s36, s27, s34
	s_cselect_b32 s35, s19, s68
	s_cselect_b32 s34, s64, s65
	v_lshl_add_u64 v[214:215], s[30:31], 0, v[184:185]
	s_add_i32 m0, s29, 0xc000
	s_nop 0
	global_load_lds_dwordx4 v[214:215], off
	v_lshl_add_u64 v[214:215], s[30:31], 0, v[186:187]
	s_add_i32 m0, s29, 0xe000
	s_nop 0
	global_load_lds_dwordx4 v[214:215], off
	ds_read_b128 v[128:131], v207
	ds_read_b128 v[132:135], v207 offset:1024
	ds_read_b128 v[136:139], v207 offset:2048
	ds_read_b128 v[140:143], v207 offset:3072
	ds_read_b128 v[144:147], v208
	ds_read_b128 v[148:151], v208 offset:1024
	ds_read_b128 v[152:155], v208 offset:2048
	ds_read_b128 v[156:159], v208 offset:3072
	ds_read_b128 v[160:163], v209
	ds_read_b128 v[164:167], v209 offset:1024
	ds_read_b128 v[168:171], v209 offset:2048
	ds_read_b128 v[172:175], v209 offset:3072
	ds_read_b128 v[192:195], v209 offset:4096
	ds_read_b128 v[196:199], v209 offset:5120
	ds_read_b128 v[200:203], v209 offset:6144
	ds_read_b128 v[210:213], v209 offset:7168
	s_nop 0
	s_nop 0
	s_waitcnt vmcnt(8)
	s_waitcnt lgkmcnt(0)
	s_setprio 1
	s_barrier
	v_mfma_f32_16x16x32_bf16 v[124:127], v[128:131], v[160:163], v[124:127]
	v_mfma_f32_16x16x32_bf16 v[120:123], v[136:139], v[160:163], v[120:123]
	v_mfma_f32_16x16x32_bf16 v[108:111], v[128:131], v[168:171], v[108:111]
	v_mfma_f32_16x16x32_bf16 v[104:107], v[136:139], v[168:171], v[104:107]
	v_mfma_f32_16x16x32_bf16 v[92:95], v[128:131], v[192:195], v[92:95]
	v_mfma_f32_16x16x32_bf16 v[88:91], v[136:139], v[192:195], v[88:91]
	v_mfma_f32_16x16x32_bf16 v[76:79], v[128:131], v[200:203], v[76:79]
	v_mfma_f32_16x16x32_bf16 v[72:75], v[136:139], v[200:203], v[72:75]
	v_mfma_f32_16x16x32_bf16 v[124:127], v[132:135], v[164:167], v[124:127]
	v_mfma_f32_16x16x32_bf16 v[120:123], v[140:143], v[164:167], v[120:123]
	v_mfma_f32_16x16x32_bf16 v[108:111], v[132:135], v[172:175], v[108:111]
	v_mfma_f32_16x16x32_bf16 v[104:107], v[140:143], v[172:175], v[104:107]
	v_mfma_f32_16x16x32_bf16 v[92:95], v[132:135], v[196:199], v[92:95]
	v_mfma_f32_16x16x32_bf16 v[88:91], v[140:143], v[196:199], v[88:91]
	v_mfma_f32_16x16x32_bf16 v[76:79], v[132:135], v[210:213], v[76:79]
	v_mfma_f32_16x16x32_bf16 v[72:75], v[140:143], v[210:213], v[72:75]
	s_setprio 0
	s_setprio 1
	v_mfma_f32_16x16x32_bf16 v[116:119], v[144:147], v[160:163], v[116:119]
	v_mfma_f32_16x16x32_bf16 v[112:115], v[152:155], v[160:163], v[112:115]
	v_mfma_f32_16x16x32_bf16 v[100:103], v[144:147], v[168:171], v[100:103]
	v_mfma_f32_16x16x32_bf16 v[96:99], v[152:155], v[168:171], v[96:99]
	v_mfma_f32_16x16x32_bf16 v[84:87], v[144:147], v[192:195], v[84:87]
	v_mfma_f32_16x16x32_bf16 v[80:83], v[152:155], v[192:195], v[80:83]
	v_mfma_f32_16x16x32_bf16 v[68:71], v[144:147], v[200:203], v[68:71]
	v_mfma_f32_16x16x32_bf16 v[64:67], v[152:155], v[200:203], v[64:67]
	v_mfma_f32_16x16x32_bf16 v[116:119], v[148:151], v[164:167], v[116:119]
	v_mfma_f32_16x16x32_bf16 v[112:115], v[156:159], v[164:167], v[112:115]
	v_mfma_f32_16x16x32_bf16 v[100:103], v[148:151], v[172:175], v[100:103]
	v_mfma_f32_16x16x32_bf16 v[96:99], v[156:159], v[172:175], v[96:99]
	v_mfma_f32_16x16x32_bf16 v[84:87], v[148:151], v[196:199], v[84:87]
	v_mfma_f32_16x16x32_bf16 v[80:83], v[156:159], v[196:199], v[80:83]
	v_mfma_f32_16x16x32_bf16 v[68:71], v[148:151], v[210:213], v[68:71]
	v_mfma_f32_16x16x32_bf16 v[64:67], v[156:159], v[210:213], v[64:67]
	s_barrier
	s_setprio 0
	s_add_i32 s70, s62, s40
	v_lshl_add_u64 v[214:215], s[34:35], 0, v[178:179]
	s_mov_b32 m0, s70
	s_nop 0
	global_load_lds_dwordx4 v[214:215], off
	s_add_i32 m0, s70, 0x2000
	s_add_u32 s70, s34, 0x40000
	v_lshl_add_u64 v[216:217], s[34:35], 0, v[182:183]
	s_addc_u32 s71, s35, 0
	s_add_i32 s72, s63, s40
	global_load_lds_dwordx4 v[216:217], off
	v_lshl_add_u64 v[218:219], s[70:71], 0, v[178:179]
	s_mov_b32 m0, s72
	v_lshl_add_u64 v[220:221], s[36:37], 0, v[180:181]
	global_load_lds_dwordx4 v[218:219], off
	v_lshl_add_u64 v[218:219], s[70:71], 0, v[182:183]
	s_add_i32 m0, s72, 0x2000
	s_nop 0
	global_load_lds_dwordx4 v[218:219], off
	v_lshl_add_u64 v[218:219], s[36:37], 0, v[176:177]
	s_mov_b32 m0, s29
	s_nop 0
	global_load_lds_dwordx4 v[218:219], off
	s_mov_b32 m0, s41
	s_nop 0
	global_load_lds_dwordx4 v[220:221], off
	ds_read_b128 v[160:163], v209 offset:16384
	ds_read_b128 v[164:167], v209 offset:17408
	ds_read_b128 v[168:171], v209 offset:18432
	ds_read_b128 v[172:175], v209 offset:19456
	ds_read_b128 v[192:195], v209 offset:20480
	ds_read_b128 v[196:199], v209 offset:21504
	ds_read_b128 v[200:203], v209 offset:22528
	ds_read_b128 v[210:213], v209 offset:23552
	s_nop 0
	s_waitcnt vmcnt(8)
	s_waitcnt lgkmcnt(0)
	s_setprio 1
	s_barrier
	v_mfma_f32_16x16x32_bf16 v[60:63], v[128:131], v[160:163], v[60:63]
	v_mfma_f32_16x16x32_bf16 v[56:59], v[136:139], v[160:163], v[56:59]
	v_mfma_f32_16x16x32_bf16 v[44:47], v[128:131], v[168:171], v[44:47]
	v_mfma_f32_16x16x32_bf16 v[40:43], v[136:139], v[168:171], v[40:43]
	v_mfma_f32_16x16x32_bf16 v[28:31], v[128:131], v[192:195], v[28:31]
	v_mfma_f32_16x16x32_bf16 v[24:27], v[136:139], v[192:195], v[24:27]
	v_mfma_f32_16x16x32_bf16 v[12:15], v[128:131], v[200:203], v[12:15]
	v_mfma_f32_16x16x32_bf16 v[8:11], v[136:139], v[200:203], v[8:11]
	v_mfma_f32_16x16x32_bf16 v[60:63], v[132:135], v[164:167], v[60:63]
	v_mfma_f32_16x16x32_bf16 v[56:59], v[140:143], v[164:167], v[56:59]
	v_mfma_f32_16x16x32_bf16 v[44:47], v[132:135], v[172:175], v[44:47]
	v_mfma_f32_16x16x32_bf16 v[40:43], v[140:143], v[172:175], v[40:43]
	v_mfma_f32_16x16x32_bf16 v[28:31], v[132:135], v[196:199], v[28:31]
	v_mfma_f32_16x16x32_bf16 v[24:27], v[140:143], v[196:199], v[24:27]
	v_mfma_f32_16x16x32_bf16 v[12:15], v[132:135], v[210:213], v[12:15]
	v_mfma_f32_16x16x32_bf16 v[8:11], v[140:143], v[210:213], v[8:11]
	s_setprio 0
	s_setprio 1
	v_mfma_f32_16x16x32_bf16 v[52:55], v[144:147], v[160:163], v[52:55]
	v_mfma_f32_16x16x32_bf16 v[48:51], v[152:155], v[160:163], v[48:51]
	v_mfma_f32_16x16x32_bf16 v[36:39], v[144:147], v[168:171], v[36:39]
	v_mfma_f32_16x16x32_bf16 v[32:35], v[152:155], v[168:171], v[32:35]
	v_mfma_f32_16x16x32_bf16 v[20:23], v[144:147], v[192:195], v[20:23]
	v_mfma_f32_16x16x32_bf16 v[16:19], v[152:155], v[192:195], v[16:19]
	v_mfma_f32_16x16x32_bf16 v[4:7], v[144:147], v[200:203], v[4:7]
	v_mfma_f32_16x16x32_bf16 v[0:3], v[152:155], v[200:203], v[0:3]
	v_mfma_f32_16x16x32_bf16 v[52:55], v[148:151], v[164:167], v[52:55]
	v_mfma_f32_16x16x32_bf16 v[48:51], v[156:159], v[164:167], v[48:51]
	v_mfma_f32_16x16x32_bf16 v[36:39], v[148:151], v[172:175], v[36:39]
	v_mfma_f32_16x16x32_bf16 v[32:35], v[156:159], v[172:175], v[32:35]
	v_mfma_f32_16x16x32_bf16 v[20:23], v[148:151], v[196:199], v[20:23]
	v_mfma_f32_16x16x32_bf16 v[16:19], v[156:159], v[196:199], v[16:19]
	v_mfma_f32_16x16x32_bf16 v[4:7], v[148:151], v[210:213], v[4:7]
	v_mfma_f32_16x16x32_bf16 v[0:3], v[156:159], v[210:213], v[0:3]
	s_barrier
	s_setprio 0
	s_add_i32 s70, 0, 0x18000
	s_add_i32 s71, 0, 0x1c000
	s_add_u32 s36, s36, 0x40000
	s_addc_u32 s37, s37, 0
	s_mov_b32 m0, s42
	v_lshl_add_u64 v[222:223], s[36:37], 0, v[176:177]
	global_load_lds_dwordx4 v[222:223], off
	v_lshl_add_u64 v[222:223], s[36:37], 0, v[180:181]
	s_mov_b32 m0, s43
	s_nop 0
	global_load_lds_dwordx4 v[222:223], off
	v_add_u32_e32 v140, s70, v206
	v_add_u32_e32 v156, s71, v206
	ds_read_b128 v[128:131], v140
	ds_read_b128 v[132:135], v140 offset:1024
	ds_read_b128 v[136:139], v140 offset:2048
	ds_read_b128 v[140:143], v140 offset:3072
	ds_read_b128 v[144:147], v156
	ds_read_b128 v[148:151], v156 offset:1024
	ds_read_b128 v[152:155], v156 offset:2048
	ds_read_b128 v[156:159], v156 offset:3072
	ds_read_b128 v[160:163], v209 offset:32768
	ds_read_b128 v[164:167], v209 offset:33792
	ds_read_b128 v[168:171], v209 offset:34816
	ds_read_b128 v[172:175], v209 offset:35840
	ds_read_b128 v[192:195], v209 offset:36864
	ds_read_b128 v[196:199], v209 offset:37888
	ds_read_b128 v[200:203], v209 offset:38912
	ds_read_b128 v[210:213], v209 offset:39936
	s_waitcnt vmcnt(8)
	s_waitcnt lgkmcnt(0)
	s_setprio 1
	s_barrier
	v_mfma_f32_16x16x32_bf16 v[124:127], v[128:131], v[160:163], v[124:127]
	v_mfma_f32_16x16x32_bf16 v[120:123], v[136:139], v[160:163], v[120:123]
	v_mfma_f32_16x16x32_bf16 v[108:111], v[128:131], v[168:171], v[108:111]
	v_mfma_f32_16x16x32_bf16 v[104:107], v[136:139], v[168:171], v[104:107]
	v_mfma_f32_16x16x32_bf16 v[92:95], v[128:131], v[192:195], v[92:95]
	v_mfma_f32_16x16x32_bf16 v[88:91], v[136:139], v[192:195], v[88:91]
	v_mfma_f32_16x16x32_bf16 v[76:79], v[128:131], v[200:203], v[76:79]
	v_mfma_f32_16x16x32_bf16 v[72:75], v[136:139], v[200:203], v[72:75]
	v_mfma_f32_16x16x32_bf16 v[124:127], v[132:135], v[164:167], v[124:127]
	v_mfma_f32_16x16x32_bf16 v[120:123], v[140:143], v[164:167], v[120:123]
	v_mfma_f32_16x16x32_bf16 v[108:111], v[132:135], v[172:175], v[108:111]
	v_mfma_f32_16x16x32_bf16 v[104:107], v[140:143], v[172:175], v[104:107]
	v_mfma_f32_16x16x32_bf16 v[92:95], v[132:135], v[196:199], v[92:95]
	v_mfma_f32_16x16x32_bf16 v[88:91], v[140:143], v[196:199], v[88:91]
	v_mfma_f32_16x16x32_bf16 v[76:79], v[132:135], v[210:213], v[76:79]
	v_mfma_f32_16x16x32_bf16 v[72:75], v[140:143], v[210:213], v[72:75]
	s_setprio 0
	s_setprio 1
	v_mfma_f32_16x16x32_bf16 v[116:119], v[144:147], v[160:163], v[116:119]
	v_mfma_f32_16x16x32_bf16 v[112:115], v[152:155], v[160:163], v[112:115]
	v_mfma_f32_16x16x32_bf16 v[100:103], v[144:147], v[168:171], v[100:103]
	v_mfma_f32_16x16x32_bf16 v[96:99], v[152:155], v[168:171], v[96:99]
	v_mfma_f32_16x16x32_bf16 v[84:87], v[144:147], v[192:195], v[84:87]
	v_mfma_f32_16x16x32_bf16 v[80:83], v[152:155], v[192:195], v[80:83]
	v_mfma_f32_16x16x32_bf16 v[68:71], v[144:147], v[200:203], v[68:71]
	v_mfma_f32_16x16x32_bf16 v[64:67], v[152:155], v[200:203], v[64:67]
	v_mfma_f32_16x16x32_bf16 v[116:119], v[148:151], v[164:167], v[116:119]
	v_mfma_f32_16x16x32_bf16 v[112:115], v[156:159], v[164:167], v[112:115]
	v_mfma_f32_16x16x32_bf16 v[100:103], v[148:151], v[172:175], v[100:103]
	v_mfma_f32_16x16x32_bf16 v[96:99], v[156:159], v[172:175], v[96:99]
	v_mfma_f32_16x16x32_bf16 v[84:87], v[148:151], v[196:199], v[84:87]
	v_mfma_f32_16x16x32_bf16 v[80:83], v[156:159], v[196:199], v[80:83]
	v_mfma_f32_16x16x32_bf16 v[68:71], v[148:151], v[210:213], v[68:71]
	v_mfma_f32_16x16x32_bf16 v[64:67], v[156:159], v[210:213], v[64:67]
	s_barrier
	s_setprio 0
	s_add_i32 s36, s70, s40
	v_lshl_add_u64 v[214:215], v[214:215], 0, s[14:15]
	s_mov_b32 m0, s36
	s_nop 0
	global_load_lds_dwordx4 v[214:215], off
	s_add_i32 m0, s36, 0x2000
	s_add_u32 s34, s34, 0x40080
	v_lshl_add_u64 v[214:215], v[216:217], 0, s[14:15]
	s_addc_u32 s35, s35, 0
	s_add_i32 s36, s71, s40
	global_load_lds_dwordx4 v[214:215], off
	v_lshl_add_u64 v[214:215], s[34:35], 0, v[178:179]
	s_mov_b32 m0, s36
	s_nop 0
	global_load_lds_dwordx4 v[214:215], off
	v_lshl_add_u64 v[214:215], s[34:35], 0, v[182:183]
	s_add_i32 m0, s36, 0x2000
	s_nop 0
	global_load_lds_dwordx4 v[214:215], off
	v_lshl_add_u64 v[214:215], v[218:219], 0, s[14:15]
	s_mov_b32 m0, s49
	s_nop 0
	global_load_lds_dwordx4 v[214:215], off
	v_lshl_add_u64 v[214:215], v[220:221], 0, s[14:15]
	s_mov_b32 m0, s50
	s_nop 0
	global_load_lds_dwordx4 v[214:215], off
	ds_read_b128 v[160:163], v209 offset:49152
	ds_read_b128 v[164:167], v209 offset:50176
	ds_read_b128 v[168:171], v209 offset:51200
	ds_read_b128 v[172:175], v209 offset:52224
	ds_read_b128 v[192:195], v209 offset:53248
	ds_read_b128 v[196:199], v209 offset:54272
	ds_read_b128 v[200:203], v209 offset:55296
	ds_read_b128 v[210:213], v209 offset:56320
	s_waitcnt vmcnt(8)
	s_waitcnt lgkmcnt(0)
	s_setprio 1
	s_barrier
	v_mfma_f32_16x16x32_bf16 v[60:63], v[128:131], v[160:163], v[60:63]
	v_mfma_f32_16x16x32_bf16 v[56:59], v[136:139], v[160:163], v[56:59]
	v_mfma_f32_16x16x32_bf16 v[44:47], v[128:131], v[168:171], v[44:47]
	v_mfma_f32_16x16x32_bf16 v[40:43], v[136:139], v[168:171], v[40:43]
	v_mfma_f32_16x16x32_bf16 v[28:31], v[128:131], v[192:195], v[28:31]
	v_mfma_f32_16x16x32_bf16 v[24:27], v[136:139], v[192:195], v[24:27]
	v_mfma_f32_16x16x32_bf16 v[12:15], v[128:131], v[200:203], v[12:15]
	v_mfma_f32_16x16x32_bf16 v[8:11], v[136:139], v[200:203], v[8:11]
	v_mfma_f32_16x16x32_bf16 v[60:63], v[132:135], v[164:167], v[60:63]
	v_mfma_f32_16x16x32_bf16 v[56:59], v[140:143], v[164:167], v[56:59]
	v_mfma_f32_16x16x32_bf16 v[44:47], v[132:135], v[172:175], v[44:47]
	v_mfma_f32_16x16x32_bf16 v[40:43], v[140:143], v[172:175], v[40:43]
	v_mfma_f32_16x16x32_bf16 v[28:31], v[132:135], v[196:199], v[28:31]
	v_mfma_f32_16x16x32_bf16 v[24:27], v[140:143], v[196:199], v[24:27]
	v_mfma_f32_16x16x32_bf16 v[12:15], v[132:135], v[210:213], v[12:15]
	v_mfma_f32_16x16x32_bf16 v[8:11], v[140:143], v[210:213], v[8:11]
	s_setprio 0
	s_setprio 1
	v_mfma_f32_16x16x32_bf16 v[52:55], v[144:147], v[160:163], v[52:55]
	v_mfma_f32_16x16x32_bf16 v[48:51], v[152:155], v[160:163], v[48:51]
	v_mfma_f32_16x16x32_bf16 v[36:39], v[144:147], v[168:171], v[36:39]
	v_mfma_f32_16x16x32_bf16 v[32:35], v[152:155], v[168:171], v[32:35]
	v_mfma_f32_16x16x32_bf16 v[20:23], v[144:147], v[192:195], v[20:23]
	v_mfma_f32_16x16x32_bf16 v[16:19], v[152:155], v[192:195], v[16:19]
	v_mfma_f32_16x16x32_bf16 v[4:7], v[144:147], v[200:203], v[4:7]
	v_mfma_f32_16x16x32_bf16 v[0:3], v[152:155], v[200:203], v[0:3]
	v_mfma_f32_16x16x32_bf16 v[52:55], v[148:151], v[164:167], v[52:55]
	v_mfma_f32_16x16x32_bf16 v[48:51], v[156:159], v[164:167], v[48:51]
	v_mfma_f32_16x16x32_bf16 v[36:39], v[148:151], v[172:175], v[36:39]
	v_mfma_f32_16x16x32_bf16 v[32:35], v[156:159], v[172:175], v[32:35]
	v_mfma_f32_16x16x32_bf16 v[20:23], v[148:151], v[196:199], v[20:23]
	v_mfma_f32_16x16x32_bf16 v[16:19], v[156:159], v[196:199], v[16:19]
	v_mfma_f32_16x16x32_bf16 v[4:7], v[148:151], v[210:213], v[4:7]
	v_mfma_f32_16x16x32_bf16 v[0:3], v[156:159], v[210:213], v[0:3]
	s_barrier
	s_setprio 0
	s_add_i32 s69, s69, 2
	s_add_u32 s30, s30, 0x100
	s_addc_u32 s31, s31, 0
	s_add_u32 s65, s65, 0x100
	s_addc_u32 s68, s68, 0
	s_cmp_gt_u32 s69, 13
	s_cbranch_scc0 .LBB0_471
	s_and_b64 vcc, exec, s[16:17]
	s_cbranch_vccz .LBB0_474
	s_barrier

.LBB0_552:
	s_add_i32 s41, s41, 1
	s_mul_i32 s6, s41, s46
	s_mul_hi_u32 s7, s41, s47
	s_add_i32 s7, s7, s6
	s_mul_i32 s6, s41, s47
	s_add_u32 s20, s6, s33
	s_addc_u32 s21, s7, s37
	v_cmp_gt_i64_e32 vcc, s[20:21], v[142:143]
	v_cmp_lt_i64_e64 s[6:7], s[20:21], v[140:141]
	s_cbranch_vccnz .LBB0_554
	s_ashr_i32 s16, s20, 31
	s_lshr_b32 s16, s16, 29
	s_add_i32 s16, s20, s16
	s_ashr_i32 s17, s16, 3
	s_and_b32 s16, s16, -8
	s_sub_i32 s16, s20, s16
	s_cmp_lt_i32 s16, 0
	s_cselect_b32 s18, s38, 0x160
	s_mul_i32 s16, s16, s18
	s_add_i32 s16, s16, s17
	s_mul_hi_i32 s17, s16, 0x2e8ba2e9
	s_lshr_b32 s18, s17, 31
	s_ashr_i32 s17, s17, 2
	s_add_i32 s17, s17, s18
	s_mul_i32 s20, s17, 22
	s_sub_i32 s20, s16, s20
	s_mov_b32 s16, s20
	s_mov_b32 s18, s17

.LBB0_631:
	s_ashr_i32 s6, s18, 3
	s_add_i32 s6, s24, s6
	s_ashr_i32 s7, s6, 31
	s_lshr_b32 s7, s7, 30
	s_add_i32 s7, s6, s7
	s_ashr_i32 s18, s7, 2
	s_and_b32 s7, s7, -4
	s_sub_i32 s6, s6, s7
	s_mov_b32 s47, s6
	s_mov_b32 s48, s18

.LBB0_720:
	s_add_i32 s73, s73, 1
	s_mul_i32 s6, s73, s84
	s_mul_hi_u32 s7, s73, s85
	s_add_i32 s7, s7, s6
	s_mul_i32 s6, s73, s85
	s_add_u32 s42, s6, s33
	s_addc_u32 s43, s7, s86
	v_mov_b64_e32 v[0:1], 0x900
	v_cmp_lt_i64_e64 s[6:7], s[42:43], v[0:1]
	v_mov_b64_e32 v[0:1], 0x8ff
	v_cmp_gt_i64_e32 vcc, s[42:43], v[0:1]
	s_cbranch_vccnz .LBB0_722
	s_ashr_i32 s9, s42, 31
	s_lshr_b32 s9, s9, 29
	s_add_i32 s9, s42, s9
	s_ashr_i32 s38, s9, 3
	s_and_b32 s9, s9, -8
	s_sub_i32 s9, s42, s9
	s_cmp_lt_i32 s9, 0
	s_cselect_b32 s39, s87, 0x120
	s_mul_i32 s9, s9, s39
	s_add_i32 s9, s9, s38
	s_mul_hi_i32 s38, s9, 0x38e38e39
	s_lshr_b32 s39, s38, 31
	s_ashr_i32 s38, s38, 2
	s_add_i32 s39, s38, s39
	s_mul_i32 s41, s39, 18
	s_sub_i32 s9, s9, s41
	s_mov_b32 s38, s9
	s_mov_b32 s40, s39

.LBB0_1107:
	s_ashr_i32 s16, s18, 3
	s_add_i32 s16, s20, s16
	s_ashr_i32 s17, s16, 31
	s_lshr_b32 s17, s17, 30
	s_add_i32 s17, s16, s17
	s_ashr_i32 s18, s17, 2
	s_and_b32 s17, s17, -4
	s_sub_i32 s17, s16, s17
	s_mov_b32 s16, s17

.LBB0_1109:
	s_add_u32 s30, s28, 0xfffc0080
	s_addc_u32 s31, s29, -1
	s_cmp_eq_u32 s64, 12
	s_cselect_b32 s35, s19, s31
	s_cselect_b32 s34, s25, s30
	s_cselect_b32 s31, s17, s63
	s_cselect_b32 s30, s61, s62
	v_lshl_add_u64 v[206:207], s[28:29], 0, v[200:201]
	s_add_i32 m0, s27, 0xc000
	s_nop 0
	global_load_lds_dwordx4 v[206:207], off
	v_lshl_add_u64 v[206:207], s[28:29], 0, v[202:203]
	s_add_i32 m0, s27, 0xe000
	s_nop 0
	global_load_lds_dwordx4 v[206:207], off
	ds_read_b128 v[120:123], v246
	ds_read_b128 v[124:127], v246 offset:1024
	ds_read_b128 v[128:131], v246 offset:2048
	ds_read_b128 v[132:135], v246 offset:3072
	ds_read_b128 v[140:143], v247
	ds_read_b128 v[148:151], v247 offset:1024
	ds_read_b128 v[152:155], v247 offset:2048
	ds_read_b128 v[156:159], v247 offset:3072
	ds_read_b128 v[160:163], v248
	ds_read_b128 v[164:167], v248 offset:1024
	ds_read_b128 v[168:171], v248 offset:2048
	ds_read_b128 v[172:175], v248 offset:3072
	ds_read_b128 v[176:179], v248 offset:4096
	ds_read_b128 v[180:183], v248 offset:5120
	ds_read_b128 v[184:187], v248 offset:6144
	ds_read_b128 v[188:191], v248 offset:7168
	s_nop 0
	s_nop 0
	s_waitcnt vmcnt(8)
	s_waitcnt lgkmcnt(0)
	s_setprio 1
	s_barrier
	v_mfma_f32_16x16x32_bf16 v[144:147], v[120:123], v[160:163], v[144:147]
	v_mfma_f32_16x16x32_bf16 v[136:139], v[128:131], v[160:163], v[136:139]
	v_mfma_f32_16x16x32_bf16 v[108:111], v[120:123], v[168:171], v[108:111]
	v_mfma_f32_16x16x32_bf16 v[104:107], v[128:131], v[168:171], v[104:107]
	v_mfma_f32_16x16x32_bf16 v[92:95], v[120:123], v[176:179], v[92:95]
	v_mfma_f32_16x16x32_bf16 v[88:91], v[128:131], v[176:179], v[88:91]
	v_mfma_f32_16x16x32_bf16 v[76:79], v[120:123], v[184:187], v[76:79]
	v_mfma_f32_16x16x32_bf16 v[72:75], v[128:131], v[184:187], v[72:75]
	v_mfma_f32_16x16x32_bf16 v[144:147], v[124:127], v[164:167], v[144:147]
	v_mfma_f32_16x16x32_bf16 v[136:139], v[132:135], v[164:167], v[136:139]
	v_mfma_f32_16x16x32_bf16 v[108:111], v[124:127], v[172:175], v[108:111]
	v_mfma_f32_16x16x32_bf16 v[104:107], v[132:135], v[172:175], v[104:107]
	v_mfma_f32_16x16x32_bf16 v[92:95], v[124:127], v[180:183], v[92:95]
	v_mfma_f32_16x16x32_bf16 v[88:91], v[132:135], v[180:183], v[88:91]
	v_mfma_f32_16x16x32_bf16 v[76:79], v[124:127], v[188:191], v[76:79]
	v_mfma_f32_16x16x32_bf16 v[72:75], v[132:135], v[188:191], v[72:75]
	s_setprio 0
	s_setprio 1
	v_mfma_f32_16x16x32_bf16 v[116:119], v[140:143], v[160:163], v[116:119]
	v_mfma_f32_16x16x32_bf16 v[112:115], v[152:155], v[160:163], v[112:115]
	v_mfma_f32_16x16x32_bf16 v[100:103], v[140:143], v[168:171], v[100:103]
	v_mfma_f32_16x16x32_bf16 v[96:99], v[152:155], v[168:171], v[96:99]
	v_mfma_f32_16x16x32_bf16 v[84:87], v[140:143], v[176:179], v[84:87]
	v_mfma_f32_16x16x32_bf16 v[80:83], v[152:155], v[176:179], v[80:83]
	v_mfma_f32_16x16x32_bf16 v[68:71], v[140:143], v[184:187], v[68:71]
	v_mfma_f32_16x16x32_bf16 v[64:67], v[152:155], v[184:187], v[64:67]
	v_mfma_f32_16x16x32_bf16 v[116:119], v[148:151], v[164:167], v[116:119]
	v_mfma_f32_16x16x32_bf16 v[112:115], v[156:159], v[164:167], v[112:115]
	v_mfma_f32_16x16x32_bf16 v[100:103], v[148:151], v[172:175], v[100:103]
	v_mfma_f32_16x16x32_bf16 v[96:99], v[156:159], v[172:175], v[96:99]
	v_mfma_f32_16x16x32_bf16 v[84:87], v[148:151], v[180:183], v[84:87]
	v_mfma_f32_16x16x32_bf16 v[80:83], v[156:159], v[180:183], v[80:83]
	v_mfma_f32_16x16x32_bf16 v[68:71], v[148:151], v[188:191], v[68:71]
	v_mfma_f32_16x16x32_bf16 v[64:67], v[156:159], v[188:191], v[64:67]
	s_barrier
	s_setprio 0
	s_add_i32 s65, s51, s37
	v_lshl_add_u64 v[206:207], s[30:31], 0, v[194:195]
	s_mov_b32 m0, s65
	s_nop 0
	global_load_lds_dwordx4 v[206:207], off
	s_add_i32 m0, s65, 0x2000
	s_add_u32 s66, s30, 0x40000
	v_lshl_add_u64 v[208:209], s[30:31], 0, v[198:199]
	s_addc_u32 s67, s31, 0
	s_add_i32 s65, s60, s37
	global_load_lds_dwordx4 v[208:209], off
	v_lshl_add_u64 v[210:211], s[66:67], 0, v[194:195]
	s_mov_b32 m0, s65
	v_lshl_add_u64 v[212:213], s[34:35], 0, v[196:197]
	global_load_lds_dwordx4 v[210:211], off
	v_lshl_add_u64 v[210:211], s[66:67], 0, v[198:199]
	s_add_i32 m0, s65, 0x2000
	s_nop 0
	global_load_lds_dwordx4 v[210:211], off
	v_lshl_add_u64 v[210:211], s[34:35], 0, v[192:193]
	s_mov_b32 m0, s27
	s_nop 0
	global_load_lds_dwordx4 v[210:211], off
	s_mov_b32 m0, s38
	s_nop 0
	global_load_lds_dwordx4 v[212:213], off
	ds_read_b128 v[160:163], v248 offset:16384
	ds_read_b128 v[164:167], v248 offset:17408
	ds_read_b128 v[168:171], v248 offset:18432
	ds_read_b128 v[172:175], v248 offset:19456
	ds_read_b128 v[176:179], v248 offset:20480
	ds_read_b128 v[180:183], v248 offset:21504
	ds_read_b128 v[184:187], v248 offset:22528
	ds_read_b128 v[188:191], v248 offset:23552
	s_nop 0
	s_waitcnt vmcnt(8)
	s_waitcnt lgkmcnt(0)
	s_setprio 1
	s_barrier
	v_mfma_f32_16x16x32_bf16 v[60:63], v[120:123], v[160:163], v[60:63]
	v_mfma_f32_16x16x32_bf16 v[56:59], v[128:131], v[160:163], v[56:59]
	v_mfma_f32_16x16x32_bf16 v[44:47], v[120:123], v[168:171], v[44:47]
	v_mfma_f32_16x16x32_bf16 v[40:43], v[128:131], v[168:171], v[40:43]
	v_mfma_f32_16x16x32_bf16 v[28:31], v[120:123], v[176:179], v[28:31]
	v_mfma_f32_16x16x32_bf16 v[24:27], v[128:131], v[176:179], v[24:27]
	v_mfma_f32_16x16x32_bf16 v[12:15], v[120:123], v[184:187], v[12:15]
	v_mfma_f32_16x16x32_bf16 v[8:11], v[128:131], v[184:187], v[8:11]
	v_mfma_f32_16x16x32_bf16 v[60:63], v[124:127], v[164:167], v[60:63]
	v_mfma_f32_16x16x32_bf16 v[56:59], v[132:135], v[164:167], v[56:59]
	v_mfma_f32_16x16x32_bf16 v[44:47], v[124:127], v[172:175], v[44:47]
	v_mfma_f32_16x16x32_bf16 v[40:43], v[132:135], v[172:175], v[40:43]
	v_mfma_f32_16x16x32_bf16 v[28:31], v[124:127], v[180:183], v[28:31]
	v_mfma_f32_16x16x32_bf16 v[24:27], v[132:135], v[180:183], v[24:27]
	v_mfma_f32_16x16x32_bf16 v[12:15], v[124:127], v[188:191], v[12:15]
	v_mfma_f32_16x16x32_bf16 v[8:11], v[132:135], v[188:191], v[8:11]
	s_setprio 0
	s_setprio 1
	v_mfma_f32_16x16x32_bf16 v[52:55], v[140:143], v[160:163], v[52:55]
	v_mfma_f32_16x16x32_bf16 v[48:51], v[152:155], v[160:163], v[48:51]
	v_mfma_f32_16x16x32_bf16 v[36:39], v[140:143], v[168:171], v[36:39]
	v_mfma_f32_16x16x32_bf16 v[32:35], v[152:155], v[168:171], v[32:35]
	v_mfma_f32_16x16x32_bf16 v[20:23], v[140:143], v[176:179], v[20:23]
	v_mfma_f32_16x16x32_bf16 v[16:19], v[152:155], v[176:179], v[16:19]
	v_mfma_f32_16x16x32_bf16 v[4:7], v[140:143], v[184:187], v[4:7]
	v_mfma_f32_16x16x32_bf16 v[0:3], v[152:155], v[184:187], v[0:3]
	v_mfma_f32_16x16x32_bf16 v[52:55], v[148:151], v[164:167], v[52:55]
	v_mfma_f32_16x16x32_bf16 v[48:51], v[156:159], v[164:167], v[48:51]
	v_mfma_f32_16x16x32_bf16 v[36:39], v[148:151], v[172:175], v[36:39]
	v_mfma_f32_16x16x32_bf16 v[32:35], v[156:159], v[172:175], v[32:35]
	v_mfma_f32_16x16x32_bf16 v[20:23], v[148:151], v[180:183], v[20:23]
	v_mfma_f32_16x16x32_bf16 v[16:19], v[156:159], v[180:183], v[16:19]
	v_mfma_f32_16x16x32_bf16 v[4:7], v[148:151], v[188:191], v[4:7]
	v_mfma_f32_16x16x32_bf16 v[0:3], v[156:159], v[188:191], v[0:3]
	s_barrier
	s_setprio 0
	s_add_i32 s65, 0, 0x18000
	s_add_i32 s66, 0, 0x1c000
	s_add_u32 s34, s34, 0x40000
	s_addc_u32 s35, s35, 0
	s_mov_b32 m0, s39
	v_lshl_add_u64 v[214:215], s[34:35], 0, v[192:193]
	global_load_lds_dwordx4 v[214:215], off
	v_lshl_add_u64 v[214:215], s[34:35], 0, v[196:197]
	s_mov_b32 m0, s40
	s_nop 0
	global_load_lds_dwordx4 v[214:215], off
	v_add_u32_e32 v132, s65, v245
	v_add_u32_e32 v156, s66, v245
	ds_read_b128 v[120:123], v132
	ds_read_b128 v[124:127], v132 offset:1024
	ds_read_b128 v[128:131], v132 offset:2048
	ds_read_b128 v[132:135], v132 offset:3072
	ds_read_b128 v[140:143], v156
	ds_read_b128 v[148:151], v156 offset:1024
	ds_read_b128 v[152:155], v156 offset:2048
	ds_read_b128 v[156:159], v156 offset:3072
	ds_read_b128 v[160:163], v248 offset:32768
	ds_read_b128 v[164:167], v248 offset:33792
	ds_read_b128 v[168:171], v248 offset:34816
	ds_read_b128 v[172:175], v248 offset:35840
	ds_read_b128 v[176:179], v248 offset:36864
	ds_read_b128 v[180:183], v248 offset:37888
	ds_read_b128 v[184:187], v248 offset:38912
	ds_read_b128 v[188:191], v248 offset:39936
	s_waitcnt vmcnt(8)
	s_waitcnt lgkmcnt(0)
	s_setprio 1
	s_barrier
	v_mfma_f32_16x16x32_bf16 v[144:147], v[120:123], v[160:163], v[144:147]
	v_mfma_f32_16x16x32_bf16 v[136:139], v[128:131], v[160:163], v[136:139]
	v_mfma_f32_16x16x32_bf16 v[108:111], v[120:123], v[168:171], v[108:111]
	v_mfma_f32_16x16x32_bf16 v[104:107], v[128:131], v[168:171], v[104:107]
	v_mfma_f32_16x16x32_bf16 v[92:95], v[120:123], v[176:179], v[92:95]
	v_mfma_f32_16x16x32_bf16 v[88:91], v[128:131], v[176:179], v[88:91]
	v_mfma_f32_16x16x32_bf16 v[76:79], v[120:123], v[184:187], v[76:79]
	v_mfma_f32_16x16x32_bf16 v[72:75], v[128:131], v[184:187], v[72:75]
	v_mfma_f32_16x16x32_bf16 v[144:147], v[124:127], v[164:167], v[144:147]
	v_mfma_f32_16x16x32_bf16 v[136:139], v[132:135], v[164:167], v[136:139]
	v_mfma_f32_16x16x32_bf16 v[108:111], v[124:127], v[172:175], v[108:111]
	v_mfma_f32_16x16x32_bf16 v[104:107], v[132:135], v[172:175], v[104:107]
	v_mfma_f32_16x16x32_bf16 v[92:95], v[124:127], v[180:183], v[92:95]
	v_mfma_f32_16x16x32_bf16 v[88:91], v[132:135], v[180:183], v[88:91]
	v_mfma_f32_16x16x32_bf16 v[76:79], v[124:127], v[188:191], v[76:79]
	v_mfma_f32_16x16x32_bf16 v[72:75], v[132:135], v[188:191], v[72:75]
	s_setprio 0
	s_setprio 1
	v_mfma_f32_16x16x32_bf16 v[116:119], v[140:143], v[160:163], v[116:119]
	v_mfma_f32_16x16x32_bf16 v[112:115], v[152:155], v[160:163], v[112:115]
	v_mfma_f32_16x16x32_bf16 v[100:103], v[140:143], v[168:171], v[100:103]
	v_mfma_f32_16x16x32_bf16 v[96:99], v[152:155], v[168:171], v[96:99]
	v_mfma_f32_16x16x32_bf16 v[84:87], v[140:143], v[176:179], v[84:87]
	v_mfma_f32_16x16x32_bf16 v[80:83], v[152:155], v[176:179], v[80:83]
	v_mfma_f32_16x16x32_bf16 v[68:71], v[140:143], v[184:187], v[68:71]
	v_mfma_f32_16x16x32_bf16 v[64:67], v[152:155], v[184:187], v[64:67]
	v_mfma_f32_16x16x32_bf16 v[116:119], v[148:151], v[164:167], v[116:119]
	v_mfma_f32_16x16x32_bf16 v[112:115], v[156:159], v[164:167], v[112:115]
	v_mfma_f32_16x16x32_bf16 v[100:103], v[148:151], v[172:175], v[100:103]
	v_mfma_f32_16x16x32_bf16 v[96:99], v[156:159], v[172:175], v[96:99]
	v_mfma_f32_16x16x32_bf16 v[84:87], v[148:151], v[180:183], v[84:87]
	v_mfma_f32_16x16x32_bf16 v[80:83], v[156:159], v[180:183], v[80:83]
	v_mfma_f32_16x16x32_bf16 v[68:71], v[148:151], v[188:191], v[68:71]
	v_mfma_f32_16x16x32_bf16 v[64:67], v[156:159], v[188:191], v[64:67]
	s_barrier
	s_setprio 0
	s_add_i32 s34, s65, s37
	v_lshl_add_u64 v[206:207], v[206:207], 0, s[12:13]
	s_mov_b32 m0, s34
	s_nop 0
	global_load_lds_dwordx4 v[206:207], off
	s_add_i32 m0, s34, 0x2000
	s_add_u32 s30, s30, 0x40080
	v_lshl_add_u64 v[206:207], v[208:209], 0, s[12:13]
	s_addc_u32 s31, s31, 0
	s_add_i32 s34, s66, s37
	global_load_lds_dwordx4 v[206:207], off
	v_lshl_add_u64 v[206:207], s[30:31], 0, v[194:195]
	s_mov_b32 m0, s34
	s_nop 0
	global_load_lds_dwordx4 v[206:207], off
	v_lshl_add_u64 v[206:207], s[30:31], 0, v[198:199]
	s_add_i32 m0, s34, 0x2000
	s_nop 0
	global_load_lds_dwordx4 v[206:207], off
	v_lshl_add_u64 v[206:207], v[210:211], 0, s[12:13]
	s_mov_b32 m0, s46
	s_nop 0
	global_load_lds_dwordx4 v[206:207], off
	v_lshl_add_u64 v[206:207], v[212:213], 0, s[12:13]
	s_mov_b32 m0, s47
	s_nop 0
	global_load_lds_dwordx4 v[206:207], off
	ds_read_b128 v[160:163], v248 offset:49152
	ds_read_b128 v[164:167], v248 offset:50176
	ds_read_b128 v[168:171], v248 offset:51200
	ds_read_b128 v[172:175], v248 offset:52224
	ds_read_b128 v[176:179], v248 offset:53248
	ds_read_b128 v[180:183], v248 offset:54272
	ds_read_b128 v[184:187], v248 offset:55296
	ds_read_b128 v[188:191], v248 offset:56320
	s_waitcnt vmcnt(8)
	s_waitcnt lgkmcnt(0)
	s_setprio 1
	s_barrier
	v_mfma_f32_16x16x32_bf16 v[60:63], v[120:123], v[160:163], v[60:63]
	v_mfma_f32_16x16x32_bf16 v[56:59], v[128:131], v[160:163], v[56:59]
	v_mfma_f32_16x16x32_bf16 v[44:47], v[120:123], v[168:171], v[44:47]
	v_mfma_f32_16x16x32_bf16 v[40:43], v[128:131], v[168:171], v[40:43]
	v_mfma_f32_16x16x32_bf16 v[28:31], v[120:123], v[176:179], v[28:31]
	v_mfma_f32_16x16x32_bf16 v[24:27], v[128:131], v[176:179], v[24:27]
	v_mfma_f32_16x16x32_bf16 v[12:15], v[120:123], v[184:187], v[12:15]
	v_mfma_f32_16x16x32_bf16 v[8:11], v[128:131], v[184:187], v[8:11]
	v_mfma_f32_16x16x32_bf16 v[60:63], v[124:127], v[164:167], v[60:63]
	v_mfma_f32_16x16x32_bf16 v[56:59], v[132:135], v[164:167], v[56:59]
	v_mfma_f32_16x16x32_bf16 v[44:47], v[124:127], v[172:175], v[44:47]
	v_mfma_f32_16x16x32_bf16 v[40:43], v[132:135], v[172:175], v[40:43]
	v_mfma_f32_16x16x32_bf16 v[28:31], v[124:127], v[180:183], v[28:31]
	v_mfma_f32_16x16x32_bf16 v[24:27], v[132:135], v[180:183], v[24:27]
	v_mfma_f32_16x16x32_bf16 v[12:15], v[124:127], v[188:191], v[12:15]
	v_mfma_f32_16x16x32_bf16 v[8:11], v[132:135], v[188:191], v[8:11]
	s_setprio 0
	s_setprio 1
	v_mfma_f32_16x16x32_bf16 v[52:55], v[140:143], v[160:163], v[52:55]
	v_mfma_f32_16x16x32_bf16 v[48:51], v[152:155], v[160:163], v[48:51]
	v_mfma_f32_16x16x32_bf16 v[36:39], v[140:143], v[168:171], v[36:39]
	v_mfma_f32_16x16x32_bf16 v[32:35], v[152:155], v[168:171], v[32:35]
	v_mfma_f32_16x16x32_bf16 v[20:23], v[140:143], v[176:179], v[20:23]
	v_mfma_f32_16x16x32_bf16 v[16:19], v[152:155], v[176:179], v[16:19]
	v_mfma_f32_16x16x32_bf16 v[4:7], v[140:143], v[184:187], v[4:7]
	v_mfma_f32_16x16x32_bf16 v[0:3], v[152:155], v[184:187], v[0:3]
	v_mfma_f32_16x16x32_bf16 v[52:55], v[148:151], v[164:167], v[52:55]
	v_mfma_f32_16x16x32_bf16 v[48:51], v[156:159], v[164:167], v[48:51]
	v_mfma_f32_16x16x32_bf16 v[36:39], v[148:151], v[172:175], v[36:39]
	v_mfma_f32_16x16x32_bf16 v[32:35], v[156:159], v[172:175], v[32:35]
	v_mfma_f32_16x16x32_bf16 v[20:23], v[148:151], v[180:183], v[20:23]
	v_mfma_f32_16x16x32_bf16 v[16:19], v[156:159], v[180:183], v[16:19]
	v_mfma_f32_16x16x32_bf16 v[4:7], v[148:151], v[188:191], v[4:7]
	v_mfma_f32_16x16x32_bf16 v[0:3], v[156:159], v[188:191], v[0:3]
	s_barrier
	s_setprio 0
	s_add_i32 s64, s64, 2
	s_add_u32 s28, s28, 0x100
	s_addc_u32 s29, s29, 0
	s_add_u32 s62, s62, 0x100
	s_addc_u32 s63, s63, 0
	s_cmp_gt_u32 s64, 13
	s_cbranch_scc0 .LBB0_1109
	s_and_b64 vcc, exec, s[14:15]
	s_cbranch_vccz .LBB0_1112
	s_barrier

.LBB0_1190:
	s_add_i32 s40, s40, 1
	s_mul_i32 s6, s40, s43
	s_mul_hi_u32 s7, s40, s46
	s_add_i32 s7, s7, s6
	s_mul_i32 s6, s40, s46
	s_add_u32 s20, s6, s33
	s_addc_u32 s21, s7, s36
	v_cmp_gt_i64_e32 vcc, s[20:21], v[142:143]
	v_cmp_lt_i64_e64 s[6:7], s[20:21], v[140:141]
	s_cbranch_vccnz .LBB0_1192
	s_ashr_i32 s16, s20, 31
	s_lshr_b32 s16, s16, 29
	s_add_i32 s16, s20, s16
	s_ashr_i32 s17, s16, 3
	s_and_b32 s16, s16, -8
	s_sub_i32 s16, s20, s16
	s_cmp_lt_i32 s16, 0
	s_cselect_b32 s18, s37, 0x160
	s_mul_i32 s16, s16, s18
	s_add_i32 s16, s16, s17
	s_mul_hi_i32 s17, s16, 0x2e8ba2e9
	s_lshr_b32 s18, s17, 31
	s_ashr_i32 s17, s17, 2
	s_add_i32 s17, s17, s18
	s_mul_i32 s20, s17, 22
	s_sub_i32 s20, s16, s20
	s_mov_b32 s16, s20
	s_mov_b32 s18, s17

.LBB0_1267:
	s_ashr_i32 s0, s14, 3
	s_add_i32 s0, s20, s0
	s_ashr_i32 s1, s0, 31
	s_lshr_b32 s1, s1, 30
	s_add_i32 s1, s0, s1
	s_ashr_i32 s14, s1, 2
	s_and_b32 s1, s1, -4
	s_sub_i32 s0, s0, s1
	s_mov_b32 s40, s0
	s_mov_b32 s41, s14
